# P1 sample-row in-projection task: operand loads issued in batches with counted waits instead of vmcnt(0) before each of 64 MFMAs (on top of v70)
# speedup vs baseline: 1.0057x; 1.0015x over previous
; __device__ __forceinline__ f32x4 mfma16(bf16x8 a, bf16x8 b, f32x4 c) { return __builtin_amdgcn_mfma_f32_16x16x32_bf16(a, b, c, 0, 0, 0); }
; template <int RT, class F>
; __device__ __forceinline__ void sample_gemm_task(const bf16* A, const bf16* Bt, int K, int ct, int row0, int lane, F f) {
;     const int l15 = lane & 15, q4 = lane >> 4;
;     f32x4 acc[RT];
; #pragma unroll
;     for (int rt = 0; rt < RT; ++rt) acc[rt] = (f32x4){0.f, 0.f, 0.f, 0.f};
;     const bf16* bp = Bt + (size_t)(16 * ct + l15) * K + 8 * q4;
;     const bf16* ap = A + (size_t)(row0 + l15) * K + 8 * q4;
; #pragma unroll 8
;     for (int ks = 0; ks < K / 32; ++ks) { const bf16x8 b = *(const bf16x8*)(bp + 32 * ks);
; #pragma unroll
;         for (int rt = 0; rt < RT; ++rt) { const bf16x8 a = *(const bf16x8*)(ap + (size_t)(16 * rt) * K + 32 * ks); acc[rt] = mfma16(a, b, acc[rt]); } }
; #pragma unroll
;     for (int rt = 0; rt < RT; ++rt)
; #pragma unroll
;         for (int r = 0; r < 4; ++r) f(row0 + 16 * rt + 4 * q4 + r, 16 * ct + l15, acc[rt][r]);
; }
.LBB0_180:
	v_lshl_add_u64 v[50:51], v[48:49], 0, s[0:1]
	v_lshl_add_u64 v[52:53], v[46:47], 0, s[0:1]
	v_add_co_u32_e32 v64, vcc, 0x100000, v50
	s_add_u32 s0, s0, 0x200
	s_addc_u32 s1, s1, 0
	v_addc_co_u32_e32 v65, vcc, 0, v51, vcc
	v_add_co_u32_e32 v50, vcc, 0x2b900000, v52
	s_cmpk_eq_i32 s0, 0x800
	s_nop 0
	v_addc_co_u32_e32 v51, vcc, 0, v53, vcc
	v_add_co_u32_e32 v52, vcc, 0x2b908000, v52
	s_nop 1
	v_addc_co_u32_e32 v53, vcc, 0, v53, vcc
	global_load_dwordx4 v[66:69], v[64:65], off
	global_load_dwordx4 v[70:73], v[64:65], off offset:64
	global_load_dwordx4 v[74:77], v[64:65], off offset:128
	global_load_dwordx4 v[78:81], v[64:65], off offset:192
	global_load_dwordx4 v[82:85], v[64:65], off offset:256
	global_load_dwordx4 v[86:89], v[64:65], off offset:320
	global_load_dwordx4 v[90:93], v[64:65], off offset:384
	global_load_dwordx4 v[94:97], v[64:65], off offset:448
	global_load_dwordx4 v[98:101], v[50:51], off
	global_load_dwordx4 v[102:105], v[52:53], off
	global_load_dwordx4 v[106:109], v[50:51], off offset:64
	global_load_dwordx4 v[110:113], v[52:53], off offset:64
	global_load_dwordx4 v[114:117], v[50:51], off offset:128
	global_load_dwordx4 v[118:121], v[52:53], off offset:128
	global_load_dwordx4 v[122:125], v[50:51], off offset:192
	global_load_dwordx4 v[126:129], v[52:53], off offset:192
	s_waitcnt vmcnt(7)
	v_mfma_f32_16x16x32_bf16 v[6:9], v[98:101], v[66:69], v[6:9]
	s_waitcnt vmcnt(6)
	v_mfma_f32_16x16x32_bf16 v[2:5], v[102:105], v[66:69], v[2:5]
	global_load_dwordx4 v[98:101], v[50:51], off offset:256
	global_load_dwordx4 v[102:105], v[52:53], off offset:256
	s_waitcnt vmcnt(7)
	v_mfma_f32_16x16x32_bf16 v[6:9], v[106:109], v[70:73], v[6:9]
	s_waitcnt vmcnt(6)
	v_mfma_f32_16x16x32_bf16 v[2:5], v[110:113], v[70:73], v[2:5]
	global_load_dwordx4 v[106:109], v[50:51], off offset:320
	global_load_dwordx4 v[110:113], v[52:53], off offset:320
	s_waitcnt vmcnt(7)
	v_mfma_f32_16x16x32_bf16 v[6:9], v[114:117], v[74:77], v[6:9]
	s_waitcnt vmcnt(6)
	v_mfma_f32_16x16x32_bf16 v[2:5], v[118:121], v[74:77], v[2:5]
	global_load_dwordx4 v[114:117], v[50:51], off offset:384
	global_load_dwordx4 v[118:121], v[52:53], off offset:384
	s_waitcnt vmcnt(7)
	v_mfma_f32_16x16x32_bf16 v[6:9], v[122:125], v[78:81], v[6:9]
	s_waitcnt vmcnt(6)
	v_mfma_f32_16x16x32_bf16 v[2:5], v[126:129], v[78:81], v[2:5]
	global_load_dwordx4 v[122:125], v[50:51], off offset:448
	global_load_dwordx4 v[126:129], v[52:53], off offset:448
	s_waitcnt vmcnt(7)
	v_mfma_f32_16x16x32_bf16 v[6:9], v[98:101], v[82:85], v[6:9]
	s_waitcnt vmcnt(6)
	v_mfma_f32_16x16x32_bf16 v[2:5], v[102:105], v[82:85], v[2:5]
	s_waitcnt vmcnt(5)
	v_mfma_f32_16x16x32_bf16 v[6:9], v[106:109], v[86:89], v[6:9]
	s_waitcnt vmcnt(4)
	v_mfma_f32_16x16x32_bf16 v[2:5], v[110:113], v[86:89], v[2:5]
	s_waitcnt vmcnt(3)
	v_mfma_f32_16x16x32_bf16 v[6:9], v[114:117], v[90:93], v[6:9]
	s_waitcnt vmcnt(2)
	v_mfma_f32_16x16x32_bf16 v[2:5], v[118:121], v[90:93], v[2:5]
	s_waitcnt vmcnt(1)
	v_mfma_f32_16x16x32_bf16 v[6:9], v[122:125], v[94:97], v[6:9]
	s_waitcnt vmcnt(0)
	v_mfma_f32_16x16x32_bf16 v[2:5], v[126:129], v[94:97], v[2:5]
	s_cbranch_scc0 .LBB0_180
	s_lshl_b32 s4, s2, 4
	v_or_b32_e32 v52, s4, v54
	s_movk_i32 s0, 0x5ff
	v_mov_b32_e32 v53, v131
	v_cmp_lt_i32_e64 s[0:1], s0, v52
	s_cmpk_gt_u32 s4, 0xbff
	v_lshlrev_b64 v[48:49], 1, v[52:53]
	s_cselect_b64 s[4:5], -1, 0
	v_lshl_add_u64 v[50:51], s[28:29], 0, v[48:49]
	v_lshl_add_u64 v[48:49], s[26:27], 0, v[48:49]
	v_cvt_pk_bf16_f32 v6, v6, s0
	s_and_saveexec_b64 s[10:11], s[0:1]
	s_xor_b64 s[48:49], exec, s[10:11]
	s_cbranch_execz .LBB0_186
	s_mov_b64 s[52:53], -1
	s_and_b64 vcc, exec, s[4:5]
	s_cbranch_vccz .LBB0_184
	v_lshl_add_u64 v[56:57], v[50:51], 0, v[10:11]
	v_add_co_u32_e32 v56, vcc, 0xfffff000, v56
	s_mov_b64 s[52:53], 0
	s_nop 0
	v_addc_co_u32_e32 v57, vcc, -1, v57, vcc
	global_store_short v[56:57], v6, off offset:-2048
